# FINMID barrier is execution-only on the hand-written final-norm path: skip its buffer_wbl2 (no data crosses that barrier)
# baseline (speedup 1.0000x reference)
; __device__ __forceinline__ unsigned xb_add(unsigned* p, unsigned v) { return __hip_atomic_fetch_add(p, v, __ATOMIC_RELAXED, __HIP_MEMORY_SCOPE_AGENT); }
; __device__ __forceinline__ void xcd_barrier(const XcdBarrier& b, int wv) {
;     ...
;         const unsigned old = xb_add(&bar[XB_XSUB(bx)], 1u);
;         const unsigned gen = old / nloc;
;         if (old + 1u == (gen + 1u) * nloc) {
;             __builtin_amdgcn_fence(__ATOMIC_RELEASE, "agent");
;             asm volatile("s_waitcnt vmcnt(0)" ::: "memory");
;             const unsigned og = xb_add(&bar[XB_TOP], 1u);
.LBB0_832:
	s_andn2_saveexec_b64 s[8:9], s[8:9]
	s_cbranch_execz .LBB0_852
	s_mov_b64 s[8:9], exec
	s_cmpk_eq_u32 s34, 0x100
	s_cbranch_scc1 .Lfinmid_nowb
	buffer_wbl2 sc1
.Lfinmid_nowb:
	s_waitcnt lgkmcnt(0)
	s_waitcnt vmcnt(0)
	v_mbcnt_lo_u32_b32 v5, s8, 0
	v_mbcnt_hi_u32_b32 v5, s9, v5
	v_cmp_eq_u32_e32 vcc, 0, v5
	s_and_saveexec_b64 s[10:11], vcc
	s_cbranch_execz .LBB0_835
	s_bcnt1_i32_b64 s8, s[8:9]
	v_mov_b32_e32 v7, s8
	v_readlane_b32 s8, v254, 3
	v_mov_b32_e32 v6, 0
	v_readlane_b32 s9, v254, 4
	s_nop 4
	global_atomic_add v6, v6, v7, s[8:9] sc0
